# attention inner loop: second-half Q.K fragment LDS reads issued up front into spare registers (on top of the moved row-sum adds)
# baseline (speedup 1.0000x reference)
; #define LAS __attribute__((address_space(3)))
; DI void attn_phase(const bf16_t* Qb, const bf16_t* Kb, const bf16_t* VT, bf16_t* MIX, LAS unsigned char* lds, int G, int bid, int tid, int wave, int lane) {
;     ...
;         auto qk = [&](f32x16& s0, f32x16& s1, const int kbuf) __attribute__((always_inline)) {
;             const LAS unsigned char* Kl = lds + kbuf * AT_KB;
;             f32x16 z;
; #pragma unroll
;             for (int r = 0; r < 16; ++r) z[r] = 0.f;
; #pragma unroll
;             for (int d0 = 0; d0 < 6; ++d0) {
;                 const bf16x8 a0 = *(const LAS bf16x8*)(Kl + r32 * 208 + d0 * 32 + hi * 16);
;                 const bf16x8 a1 = *(const LAS bf16x8*)(Kl + (32 + r32) * 208 + d0 * 32 + hi * 16);
;                 if (d0 == 0) { s0 = MFMA32(a0, qf[0], z); s1 = MFMA32(a1, qf[0], z); }
;                 else { s0 = MFMA32(a0, qf[d0], s0); s1 = MFMA32(a1, qf[d0], s1); }
;             }
;         };
;         auto softmax_pack = [&](f32x16& s0, f32x16& s1, bf16x8 (&pa)[4]) __attribute__((always_inline)) {
;             float ps0 = 0.f, ps1 = 0.f;
; #pragma unroll
;             for (int r = 0; r < 16; ++r) { s0[r] = __builtin_amdgcn_exp2f(s0[r]); s1[r] = __builtin_amdgcn_exp2f(s1[r]); ps0 += s0[r]; ps1 += s1[r]; }
;             lsum += ps0 + ps1;
;             u32x4 w;
;             w.x = pk2(s0[0], s0[1]); w.y = pk2(s0[2], s0[3]); w.z = pk2(s0[4], s0[5]); w.w = pk2(s0[6], s0[7]); pa[0] = __builtin_bit_cast(bf16x8, w);
;             w.x = pk2(s0[8], s0[9]); w.y = pk2(s0[10], s0[11]); w.z = pk2(s0[12], s0[13]); w.w = pk2(s0[14], s0[15]); pa[1] = __builtin_bit_cast(bf16x8, w);
;             w.x = pk2(s1[0], s1[1]); w.y = pk2(s1[2], s1[3]); w.z = pk2(s1[4], s1[5]); w.w = pk2(s1[6], s1[7]); pa[2] = __builtin_bit_cast(bf16x8, w);
;             w.x = pk2(s1[8], s1[9]); w.y = pk2(s1[10], s1[11]); w.z = pk2(s1[12], s1[13]); w.w = pk2(s1[14], s1[15]); pa[3] = __builtin_bit_cast(bf16x8, w);
;         };
;         auto pv = [&](const bf16x8 (&pa)[4], const int vbuf) __attribute__((always_inline)) {
;             const LAS unsigned char* Vl = lds + 2 * AT_KB + vbuf * AT_VB;
; #pragma unroll
;             for (int kk = 0; kk < 4; ++kk) {
;                 const LAS unsigned char* vp = Vl + r32 * 144 + kk * 32 + hi * 16;
;                 const bf16x8 b0 = *(const LAS bf16x8*)(vp);
;                 const bf16x8 b1 = *(const LAS bf16x8*)(vp + 32 * 144);
.LBB0_454:
	ds_read_b128 v[64:67], v219 offset:13312
	ds_read_b128 v[132:135], v219 offset:13344
	s_nop 4
	v_exp_f32_e32 v169, v48
	v_exp_f32_e32 v171, v49
	v_exp_f32_e32 v173, v50
	s_waitcnt lgkmcnt(1)
	v_mfma_f32_32x32x16_bf16 v[80:95], v[64:67], v[128:131], 0
	ds_read_b128 v[64:67], v219 offset:19968
	ds_read_b128 v[136:139], v219 offset:20000
	v_exp_f32_e32 v175, v51
	v_exp_f32_e32 v177, v52
	v_exp_f32_e32 v181, v53
	v_exp_f32_e32 v183, v54
	v_exp_f32_e32 v185, v55
	v_cvt_pk_bf16_f32 v48, v169, v171
	s_waitcnt lgkmcnt(1)
	v_mfma_f32_32x32x16_bf16 v[64:79], v[64:67], v[128:131], 0
	v_cvt_pk_bf16_f32 v49, v173, v175
	v_cvt_pk_bf16_f32 v50, v177, v181
	v_cvt_pk_bf16_f32 v51, v183, v185
	v_exp_f32_e32 v179, v56
	v_exp_f32_e32 v191, v57
	v_exp_f32_e32 v189, v58
	v_exp_f32_e32 v187, v59
	v_mfma_f32_32x32x16_bf16 v[80:95], v[132:135], v[124:127], v[80:95]
	v_exp_f32_e32 v195, v60
	v_exp_f32_e32 v193, v61
	v_exp_f32_e32 v221, v62
	v_exp_f32_e32 v197, v63
	v_cvt_pk_bf16_f32 v60, v179, v191
	v_cvt_pk_bf16_f32 v61, v189, v187
	v_cvt_pk_bf16_f32 v62, v195, v193
	s_waitcnt lgkmcnt(0)
	v_mfma_f32_32x32x16_bf16 v[64:79], v[136:139], v[124:127], v[64:79]
	ds_read_b128 v[132:135], v219 offset:13376
	ds_read_b128 v[136:139], v219 offset:13408
	v_cvt_pk_bf16_f32 v63, v221, v197
	v_exp_f32_e32 v229, v32
	v_exp_f32_e32 v227, v33
	v_exp_f32_e32 v225, v34
	v_exp_f32_e32 v223, v35
	v_exp_f32_e32 v230, v36
	s_waitcnt lgkmcnt(1)
	v_mfma_f32_32x32x16_bf16 v[80:95], v[132:135], v[120:123], v[80:95]
	ds_read_b128 v[132:135], v219 offset:20032
	ds_read_b128 v[140:143], v219 offset:20064
	v_exp_f32_e32 v228, v37
	v_exp_f32_e32 v226, v38
	v_exp_f32_e32 v224, v39
	v_cvt_pk_bf16_f32 v32, v229, v227
	v_cvt_pk_bf16_f32 v33, v225, v223
	v_cvt_pk_bf16_f32 v34, v230, v228
	s_waitcnt lgkmcnt(1)
	v_mfma_f32_32x32x16_bf16 v[64:79], v[132:135], v[120:123], v[64:79]
	v_cvt_pk_bf16_f32 v35, v226, v224
	s_add_i32 s20, s38, -1
	s_min_u32 s39, s20, s31
	v_exp_f32_e32 v222, v40
	v_exp_f32_e32 v233, v41
	v_exp_f32_e32 v232, v42
	v_exp_f32_e32 v231, v43
	v_mfma_f32_32x32x16_bf16 v[80:95], v[136:139], v[116:119], v[80:95]
	ds_read_b128 v[132:135], v219 offset:13440
	ds_read_b128 v[136:139], v219 offset:13472
	s_mul_i32 s20, s39, 0x1800
	s_lshl_b64 s[26:27], s[20:21], 1
	s_add_u32 s26, s8, s26
	s_addc_u32 s27, s9, s27
	v_exp_f32_e32 v235, v44
	v_exp_f32_e32 v234, v45
	s_waitcnt lgkmcnt(2)
	v_mfma_f32_32x32x16_bf16 v[64:79], v[140:143], v[116:119], v[64:79]
	v_exp_f32_e32 v237, v46
	v_exp_f32_e32 v236, v47
	v_cvt_pk_bf16_f32 v44, v222, v233
	v_cvt_pk_bf16_f32 v45, v232, v231
	v_cvt_pk_bf16_f32 v46, v235, v234
	v_cvt_pk_bf16_f32 v47, v237, v236
	s_waitcnt lgkmcnt(1)
	v_mfma_f32_32x32x16_bf16 v[80:95], v[132:135], v[108:111], v[80:95]
	ds_read_b128 v[132:135], v219 offset:20096
	ds_read_b128 v[140:143], v219 offset:20128
	ds_read_b128 v[52:55], v220 offset:26624
	ds_read_b128 v[56:59], v220 offset:26656
	ds_read_b128 v[36:39], v220 offset:26688
	ds_read_b128 v[40:43], v220 offset:26720
	s_waitcnt lgkmcnt(3)
	v_mfma_f32_32x32x16_bf16 v[16:31], v[48:51], v[52:55], v[16:31]
	v_add_f32_e32 v241, 0, v169
	v_add_f32_e32 v242, 0, v229
	v_add_f32_e32 v241, v171, v241
	v_add_f32_e32 v242, v227, v242
	ds_read_b128 v[52:55], v220 offset:31232
	v_mfma_f32_32x32x16_bf16 v[64:79], v[132:135], v[108:111], v[64:79]
	ds_read_b128 v[132:135], v220 offset:31264
	s_waitcnt lgkmcnt(1)
	v_mfma_f32_32x32x16_bf16 v[0:15], v[48:51], v[52:55], v[0:15]
	v_add_f32_e32 v241, v173, v241
	v_add_f32_e32 v242, v225, v242
	v_add_f32_e32 v241, v175, v241
	v_add_f32_e32 v242, v223, v242
	ds_read_b128 v[48:51], v220 offset:31328
	v_mfma_f32_32x32x16_bf16 v[16:31], v[60:63], v[56:59], v[16:31]
	v_add_f32_e32 v241, v177, v241
	v_add_f32_e32 v242, v230, v242
	v_add_f32_e32 v241, v181, v241
	v_add_f32_e32 v242, v228, v242
	s_waitcnt lgkmcnt(1)
	v_mfma_f32_32x32x16_bf16 v[0:15], v[60:63], v[132:135], v[0:15]
	v_add_f32_e32 v241, v183, v241
	v_add_f32_e32 v242, v226, v242
	v_add_f32_e32 v241, v185, v241
	v_add_f32_e32 v242, v224, v242
	v_mfma_f32_32x32x16_bf16 v[16:31], v[32:35], v[36:39], v[16:31]
	v_add_f32_e32 v241, v179, v241
	v_add_f32_e32 v242, v222, v242
	v_add_f32_e32 v241, v191, v241
	v_add_f32_e32 v242, v233, v242
	ds_read_b128 v[36:39], v220 offset:31296
	s_waitcnt lgkmcnt(0)
	v_mfma_f32_32x32x16_bf16 v[0:15], v[32:35], v[36:39], v[0:15]
	v_add_f32_e32 v241, v189, v241
	v_add_f32_e32 v242, v232, v242
	v_add_f32_e32 v241, v187, v241
	v_add_f32_e32 v242, v231, v242
	v_lshl_add_u64 v[32:33], v[160:161], 1, s[26:27]
	v_mfma_f32_32x32x16_bf16 v[80:95], v[136:139], v[100:103], v[80:95]
	v_mfma_f32_32x32x16_bf16 v[64:79], v[140:143], v[100:103], v[64:79]
	global_load_dwordx4 v[140:143], v[32:33], off
	global_load_dwordx4 v[136:139], v215, s[26:27]
	global_load_dwordx4 v[132:135], v[200:201], off
	s_waitcnt vmcnt(4)
	ds_write_b128 v216, v[112:115]
	v_mfma_f32_32x32x16_bf16 v[16:31], v[44:47], v[40:43], v[16:31]
	v_add_f32_e32 v241, v195, v241
	v_add_f32_e32 v242, v235, v242
	v_add_f32_e32 v241, v193, v241
	v_add_f32_e32 v242, v234, v242
	v_add_f32_e32 v241, v221, v241
	v_mfma_f32_32x32x16_bf16 v[0:15], v[44:47], v[48:51], v[0:15]
	v_add_f32_e32 v242, v237, v242
	v_add_f32_e32 v241, v197, v241
	v_add_f32_e32 v242, v236, v242
	v_add_f32_e32 v241, v241, v242
	v_add_f32_e32 v167, v167, v241
	s_and_saveexec_b64 s[26:27], s[4:5]
	ds_write_b128 v218, v[104:107]
	s_or_b64 exec, exec, s[26:27]
	s_waitcnt vmcnt(3)
	ds_write_b128 v217, v[96:99] offset:35840
	s_waitcnt lgkmcnt(0)
	s_barrier
; #define LAS __attribute__((address_space(3)))
; DI void attn_phase(const bf16_t* Qb, const bf16_t* Kb, const bf16_t* VT, bf16_t* MIX, LAS unsigned char* lds, int G, int bid, int tid, int wave, int lane) {
;     ...
;         auto qk = [&](f32x16& s0, f32x16& s1, const int kbuf) __attribute__((always_inline)) {
;             const LAS unsigned char* Kl = lds + kbuf * AT_KB;
;             f32x16 z;
; #pragma unroll
;             for (int r = 0; r < 16; ++r) z[r] = 0.f;
; #pragma unroll
;             for (int d0 = 0; d0 < 6; ++d0) {
;                 const bf16x8 a0 = *(const LAS bf16x8*)(Kl + r32 * 208 + d0 * 32 + hi * 16);
;                 const bf16x8 a1 = *(const LAS bf16x8*)(Kl + (32 + r32) * 208 + d0 * 32 + hi * 16);
;                 if (d0 == 0) { s0 = MFMA32(a0, qf[0], z); s1 = MFMA32(a1, qf[0], z); }
;                 else { s0 = MFMA32(a0, qf[d0], s0); s1 = MFMA32(a1, qf[d0], s1); }
;             }
;         };
;         auto softmax_pack = [&](f32x16& s0, f32x16& s1, bf16x8 (&pa)[4]) __attribute__((always_inline)) {
;             float ps0 = 0.f, ps1 = 0.f;
; #pragma unroll
;             for (int r = 0; r < 16; ++r) { s0[r] = __builtin_amdgcn_exp2f(s0[r]); s1[r] = __builtin_amdgcn_exp2f(s1[r]); ps0 += s0[r]; ps1 += s1[r]; }
;             lsum += ps0 + ps1;
;             u32x4 w;
;             w.x = pk2(s0[0], s0[1]); w.y = pk2(s0[2], s0[3]); w.z = pk2(s0[4], s0[5]); w.w = pk2(s0[6], s0[7]); pa[0] = __builtin_bit_cast(bf16x8, w);
;             w.x = pk2(s0[8], s0[9]); w.y = pk2(s0[10], s0[11]); w.z = pk2(s0[12], s0[13]); w.w = pk2(s0[14], s0[15]); pa[1] = __builtin_bit_cast(bf16x8, w);
;             w.x = pk2(s1[0], s1[1]); w.y = pk2(s1[2], s1[3]); w.z = pk2(s1[4], s1[5]); w.w = pk2(s1[6], s1[7]); pa[2] = __builtin_bit_cast(bf16x8, w);
;             w.x = pk2(s1[8], s1[9]); w.y = pk2(s1[10], s1[11]); w.z = pk2(s1[12], s1[13]); w.w = pk2(s1[14], s1[15]); pa[3] = __builtin_bit_cast(bf16x8, w);
;         };
;         auto pv = [&](const bf16x8 (&pa)[4], const int vbuf) __attribute__((always_inline)) {
;             const LAS unsigned char* Vl = lds + 2 * AT_KB + vbuf * AT_VB;
; #pragma unroll
;             for (int kk = 0; kk < 4; ++kk) {
;                 const LAS unsigned char* vp = Vl + r32 * 144 + kk * 32 + hi * 16;
;                 const bf16x8 b0 = *(const LAS bf16x8*)(vp);
;                 const bf16x8 b1 = *(const LAS bf16x8*)(vp + 32 * 144);
	ds_read_b128 v[32:35], v219
	ds_read_b128 v[96:99], v219 offset:32
	ds_read_b128 v[222:225], v219 offset:6656
	ds_read_b128 v[226:229], v219 offset:6688
	ds_read_b128 v[230:233], v219 offset:64
	ds_read_b128 v[234:237], v219 offset:6720
	ds_read_b128 v[244:247], v219 offset:96
	v_exp_f32_e32 v80, v80
	v_exp_f32_e32 v81, v81
	v_exp_f32_e32 v82, v82
	s_waitcnt lgkmcnt(6)
	v_mfma_f32_32x32x16_bf16 v[48:63], v[32:35], v[128:131], 0
	v_exp_f32_e32 v83, v83
	v_exp_f32_e32 v84, v84
	v_exp_f32_e32 v85, v85
	v_exp_f32_e32 v86, v86
	v_exp_f32_e32 v87, v87
	v_exp_f32_e32 v239, v88
	s_waitcnt lgkmcnt(5)
	v_mfma_f32_32x32x16_bf16 v[48:63], v[96:99], v[124:127], v[48:63]
	ds_read_b128 v[96:99], v219 offset:6752
	v_exp_f32_e32 v238, v89
	v_exp_f32_e32 v89, v90
	v_exp_f32_e32 v88, v91
	v_exp_f32_e32 v91, v92
	v_exp_f32_e32 v93, v93
	v_exp_f32_e32 v92, v94
	s_waitcnt lgkmcnt(5)
	v_mfma_f32_32x32x16_bf16 v[32:47], v[222:225], v[128:131], 0
	ds_read_b128 v[222:225], v219 offset:128
	v_exp_f32_e32 v90, v95
	v_cvt_pk_bf16_f32 v202, v239, v238
	v_cvt_pk_bf16_f32 v203, v89, v88
	v_cvt_pk_bf16_f32 v204, v91, v93
	v_cvt_pk_bf16_f32 v205, v92, v90
	v_exp_f32_e32 v95, v64
	v_exp_f32_e32 v94, v65
	s_waitcnt lgkmcnt(5)
	v_mfma_f32_32x32x16_bf16 v[32:47], v[226:229], v[124:127], v[32:47]
	ds_read_b128 v[226:229], v219 offset:6784
	v_exp_f32_e32 v66, v66
	v_exp_f32_e32 v240, v67
	v_exp_f32_e32 v68, v68
	v_exp_f32_e32 v67, v69
	v_exp_f32_e32 v65, v70
	v_exp_f32_e32 v64, v71
	s_waitcnt lgkmcnt(5)
	v_mfma_f32_32x32x16_bf16 v[48:63], v[230:233], v[120:123], v[48:63]
	ds_read_b128 v[230:233], v219 offset:160
	v_exp_f32_e32 v72, v72
	v_exp_f32_e32 v71, v73
	v_exp_f32_e32 v70, v74
	v_exp_f32_e32 v69, v75
	v_exp_f32_e32 v74, v76
	v_exp_f32_e32 v76, v77
	s_waitcnt lgkmcnt(5)
	v_mfma_f32_32x32x16_bf16 v[32:47], v[234:237], v[120:123], v[32:47]
	ds_read_b128 v[104:107], v219 offset:6816
	v_exp_f32_e32 v75, v78
	v_exp_f32_e32 v73, v79
	s_min_u32 s20, s38, s31
	s_mulk_i32 s20, 0x3000
	s_add_u32 s26, s8, s20
	s_addc_u32 s27, s9, 0
	s_waitcnt lgkmcnt(5)
	v_mfma_f32_32x32x16_bf16 v[48:63], v[244:247], v[116:119], v[48:63]
	ds_read_b128 v[112:115], v220 offset:40448
	v_lshl_add_u64 v[78:79], v[160:161], 1, s[26:27]
	s_lshl_b32 s20, s39, 7
	v_lshl_add_u64 v[206:207], v[198:199], 0, s[20:21]
	s_waitcnt lgkmcnt(5)
	v_mfma_f32_32x32x16_bf16 v[32:47], v[96:99], v[116:119], v[32:47]
	s_waitcnt lgkmcnt(4)
	v_mfma_f32_32x32x16_bf16 v[48:63], v[222:225], v[108:111], v[48:63]
	s_waitcnt lgkmcnt(3)
	v_mfma_f32_32x32x16_bf16 v[32:47], v[226:229], v[108:111], v[32:47]
	s_waitcnt lgkmcnt(2)
	v_mfma_f32_32x32x16_bf16 v[48:63], v[230:233], v[100:103], v[48:63]
	v_cvt_pk_bf16_f32 v96, v80, v81
	v_cvt_pk_bf16_f32 v97, v82, v83
	v_cvt_pk_bf16_f32 v98, v84, v85
	v_cvt_pk_bf16_f32 v99, v86, v87
	s_waitcnt lgkmcnt(1)
	v_mfma_f32_32x32x16_bf16 v[32:47], v[104:107], v[100:103], v[32:47]
	ds_read_b128 v[104:107], v220 offset:35840
	s_waitcnt lgkmcnt(0)
	v_mfma_f32_32x32x16_bf16 v[16:31], v[96:99], v[104:107], v[16:31]
	v_add_f32_e32 v241, 0, v80
	v_add_f32_e32 v242, 0, v95
	v_add_f32_e32 v241, v81, v241
	v_add_f32_e32 v242, v94, v242
	ds_read_b128 v[104:107], v220 offset:35872
	v_mfma_f32_32x32x16_bf16 v[0:15], v[96:99], v[112:115], v[0:15]
	v_add_f32_e32 v241, v82, v241
	v_add_f32_e32 v242, v66, v242
	v_add_f32_e32 v241, v83, v241
	v_add_f32_e32 v242, v240, v242
	ds_read_b128 v[96:99], v220 offset:40480
	ds_read_b128 v[112:115], v220 offset:40512
	s_waitcnt lgkmcnt(1)
	v_mfma_f32_32x32x16_bf16 v[0:15], v[202:205], v[96:99], v[0:15]
	v_add_f32_e32 v241, v84, v241
	v_add_f32_e32 v242, v68, v242
	v_add_f32_e32 v241, v85, v241
	v_add_f32_e32 v242, v67, v242
	ds_read_b128 v[96:99], v220 offset:35904
	v_mfma_f32_32x32x16_bf16 v[16:31], v[202:205], v[104:107], v[16:31]
	v_add_f32_e32 v241, v86, v241
	v_add_f32_e32 v242, v65, v242
	v_add_f32_e32 v241, v87, v241
	v_add_f32_e32 v242, v64, v242
	v_cvt_pk_bf16_f32 v104, v95, v94
	v_cvt_pk_bf16_f32 v105, v66, v240
	v_cvt_pk_bf16_f32 v106, v68, v67
	v_cvt_pk_bf16_f32 v107, v65, v64
	v_cvt_pk_bf16_f32 v202, v72, v71
	v_cvt_pk_bf16_f32 v203, v70, v69
	v_cvt_pk_bf16_f32 v204, v74, v76
	s_waitcnt lgkmcnt(0)
	v_mfma_f32_32x32x16_bf16 v[16:31], v[104:107], v[96:99], v[16:31]
	v_add_f32_e32 v241, v239, v241
	v_add_f32_e32 v242, v72, v242
	v_add_f32_e32 v241, v238, v241
	v_add_f32_e32 v242, v71, v242
	ds_read_b128 v[96:99], v220 offset:35936
	v_cvt_pk_bf16_f32 v205, v75, v73
	v_mfma_f32_32x32x16_bf16 v[0:15], v[104:107], v[112:115], v[0:15]
	v_add_f32_e32 v241, v89, v241
	v_add_f32_e32 v242, v70, v242
	v_add_f32_e32 v241, v88, v241
	v_add_f32_e32 v242, v69, v242
	global_load_dwordx4 v[104:107], v215, s[26:27]
	s_waitcnt lgkmcnt(0)
	v_mfma_f32_32x32x16_bf16 v[16:31], v[202:205], v[96:99], v[16:31]
	v_add_f32_e32 v241, v91, v241
	v_add_f32_e32 v242, v74, v242
	v_add_f32_e32 v241, v93, v241
	v_add_f32_e32 v242, v76, v242
	v_add_f32_e32 v241, v92, v241
	global_load_dwordx4 v[112:115], v[78:79], off
	global_load_dwordx4 v[96:99], v[206:207], off
	ds_read_b128 v[206:209], v220 offset:40544
	s_waitcnt vmcnt(5)
	ds_write_b128 v216, v[140:143] offset:13312
	s_waitcnt lgkmcnt(1)
	v_mfma_f32_32x32x16_bf16 v[0:15], v[202:205], v[206:209], v[0:15]
	v_add_f32_e32 v242, v75, v242
	v_add_f32_e32 v241, v90, v241
	v_add_f32_e32 v242, v73, v242
	v_add_f32_e32 v241, v241, v242
	v_add_f32_e32 v167, v167, v241
	s_and_saveexec_b64 s[26:27], s[4:5]
	s_cbranch_execz .LBB0_458
	s_waitcnt vmcnt(4)
	ds_write_b128 v218, v[136:139] offset:13312
